# in-proj A: two CU groups offset 4us + write-through epilogue stores + side-job wait vmcnt(16)
# baseline (speedup 1.0000x reference)
; __device__ __forceinline__ float sum_x16(float v) { float a, b; swap16(v, a, b); return a + b; }
; __device__ __forceinline__ float sum_x32(float v) { float a, b; swap32(v, a, b); return a + b; }
; __device__ __forceinline__ void st16_wt(void* p, u32x4 v) { if (WT_STORES) asm volatile("global_store_dwordx4 %0, %1, off sc1\n\ts_nop 1" :: "v"(p), "v"(v) : "memory"); else *(u32x4*)p = v; }
; __device__ __forceinline__ unsigned cvt_pk_bf16(float lo, float hi) { unsigned r; asm volatile("v_cvt_pk_bf16_f32 %0, %1, %2" : "=v"(r) : "v"(lo), "v"(hi)); return r; }
;     __device__ __forceinline__ void operator()(const f32x4 (&acc)[2][2][4][2], const Unit& u, int wr, int wc, int fr, int fq, const bool reuse, PG8_LAS float* rscr, PG8_LAS const float* gains) const {
;     ...
;                 if (type < 2) {
;                     float ss = 0.f;
; #pragma unroll
;                     for (int bj = 0; bj < 2; ++bj)
; #pragma unroll
;                         for (int n = 0; n < 2; ++n) { const f32x4 x = v[bj][n]; ss += (x[0] * x[0] + x[1] * x[1]) + (x[2] * x[2] + x[3] * x[3]); }
;                     ss = sum_x16(ss); ss = sum_x32(ss);
;                     const float inv = __builtin_amdgcn_rsqf(ss * (1.0f / 64.0f) + RMS_EPS);
; #pragma unroll
;                     for (int bj = 0; bj < 2; ++bj)
; #pragma unroll
;                         for (int n = 0; n < 2; ++n) v[bj][n] = v[bj][n] * gv[bj][n] * inv;
;                 }
;                 bf16_t* p = p0 + (size_t)(8 * ai + m) * step16;
; #pragma unroll
;                 for (int bj = 0; bj < 2; ++bj) { u32x4 w; w.x = cvt_pk_bf16(v[bj][0][0], v[bj][0][1]); w.y = cvt_pk_bf16(v[bj][0][2], v[bj][0][3]); w.z = cvt_pk_bf16(v[bj][1][0], v[bj][1][1]); w.w = cvt_pk_bf16(v[bj][1][2], v[bj][1][3]);
;                     st16_wt(p + 32 * bj, w); }
.LBB0_232:
	v_lshl_add_u64 v[186:187], v[186:187], 0, v[160:161]
	s_and_b64 vcc, exec, s[38:39]
	v_cvt_pk_bf16_f32 v132, v132, v133
	v_cvt_pk_bf16_f32 v133, v134, v135
	v_cvt_pk_bf16_f32 v134, v128, v129
	v_cvt_pk_bf16_f32 v135, v130, v131
	global_store_dwordx4 v[186:187], v[132:135], off sc1
	v_cvt_pk_bf16_f32 v128, v140, v141
	v_cvt_pk_bf16_f32 v129, v142, v143
	v_cvt_pk_bf16_f32 v130, v136, v137
	v_cvt_pk_bf16_f32 v131, v138, v139
	global_store_dwordx4 v[186:187], v[128:131], off offset:64 sc1
	s_cbranch_vccnz .LBB0_234
	s_nop 0
	v_mul_f32_e32 v128, v117, v117
	v_mul_f32_e32 v129, v119, v119
	v_fmac_f32_e32 v128, v116, v116
	v_fmac_f32_e32 v129, v118, v118
	v_add_f32_e32 v128, v128, v129
	v_mul_f32_e32 v129, v113, v113
	v_mul_f32_e32 v130, v115, v115
	v_fmac_f32_e32 v129, v112, v112
	v_fmac_f32_e32 v130, v114, v114
	v_add_f32_e32 v129, v129, v130
	v_add_f32_e32 v128, v128, v129
	v_mul_f32_e32 v129, v125, v125
	v_mul_f32_e32 v130, v127, v127
	v_fmac_f32_e32 v129, v124, v124
	v_fmac_f32_e32 v130, v126, v126
	v_add_f32_e32 v129, v129, v130
	v_add_f32_e32 v128, v128, v129
	v_mul_f32_e32 v129, v121, v121
	v_mul_f32_e32 v130, v123, v123
	v_fmac_f32_e32 v129, v120, v120
	v_fmac_f32_e32 v130, v122, v122
	v_add_f32_e32 v129, v129, v130
	v_add_f32_e32 v128, v128, v129
	v_mov_b32_e32 v129, v128
	s_nop 1
	v_permlane16_swap_b32_e32 v128, v129
	v_add_f32_e32 v128, v128, v129
	v_mov_b32_e32 v129, v128
	s_nop 1
	v_permlane32_swap_b32_e32 v128, v129
	v_add_f32_e32 v128, v128, v129
	v_fmamk_f32 v128, v128, 0x3c800000, v190
	v_rsq_f32_e32 v128, v128
	s_waitcnt lgkmcnt(0)
	v_pk_mul_f32 v[118:119], v[118:119], v[158:159]
	v_pk_mul_f32 v[116:117], v[116:117], v[156:157]
	v_pk_mul_f32 v[114:115], v[114:115], v[154:155]
	v_pk_mul_f32 v[112:113], v[112:113], v[152:153]
	v_pk_mul_f32 v[126:127], v[126:127], v[150:151]
	v_pk_mul_f32 v[124:125], v[124:125], v[148:149]
	v_pk_mul_f32 v[122:123], v[122:123], v[146:147]
	v_pk_mul_f32 v[120:121], v[120:121], v[144:145]
	v_pk_mul_f32 v[118:119], v[118:119], v[128:129] op_sel_hi:[1,0]
	v_pk_mul_f32 v[116:117], v[116:117], v[128:129] op_sel_hi:[1,0]
	v_pk_mul_f32 v[114:115], v[114:115], v[128:129] op_sel_hi:[1,0]
	v_pk_mul_f32 v[112:113], v[112:113], v[128:129] op_sel_hi:[1,0]
	v_pk_mul_f32 v[126:127], v[126:127], v[128:129] op_sel_hi:[1,0]
	v_pk_mul_f32 v[124:125], v[124:125], v[128:129] op_sel_hi:[1,0]
	v_pk_mul_f32 v[122:123], v[122:123], v[128:129] op_sel_hi:[1,0]
	v_pk_mul_f32 v[120:121], v[120:121], v[128:129] op_sel_hi:[1,0]
.LBB0_234:
	s_lshl_b32 s88, s72, 1
	v_lshl_add_u64 v[128:129], v[186:187], 0, s[88:89]
	s_and_b64 vcc, exec, s[38:39]
	v_cvt_pk_bf16_f32 v116, v116, v117
	v_cvt_pk_bf16_f32 v117, v118, v119
	v_cvt_pk_bf16_f32 v118, v112, v113
	v_cvt_pk_bf16_f32 v119, v114, v115
	global_store_dwordx4 v[128:129], v[116:119], off sc1
	v_cvt_pk_bf16_f32 v112, v124, v125
	v_cvt_pk_bf16_f32 v113, v126, v127
	v_cvt_pk_bf16_f32 v114, v120, v121
	v_cvt_pk_bf16_f32 v115, v122, v123
	global_store_dwordx4 v[128:129], v[112:115], off offset:64 sc1
	s_cbranch_vccnz .LBB0_236
	s_nop 0
	v_mul_f32_e32 v112, v101, v101
	v_mul_f32_e32 v113, v103, v103
	v_fmac_f32_e32 v112, v100, v100
	v_fmac_f32_e32 v113, v102, v102
	v_add_f32_e32 v112, v112, v113
	v_mul_f32_e32 v113, v97, v97
	v_mul_f32_e32 v114, v99, v99
	v_fmac_f32_e32 v113, v96, v96
	v_fmac_f32_e32 v114, v98, v98
	v_add_f32_e32 v113, v113, v114
	v_add_f32_e32 v112, v112, v113
	v_mul_f32_e32 v113, v109, v109
	v_mul_f32_e32 v114, v111, v111
	v_fmac_f32_e32 v113, v108, v108
	v_fmac_f32_e32 v114, v110, v110
	v_add_f32_e32 v113, v113, v114
	v_add_f32_e32 v112, v112, v113
	v_mul_f32_e32 v113, v105, v105
	v_mul_f32_e32 v114, v107, v107
	v_fmac_f32_e32 v113, v104, v104
	v_fmac_f32_e32 v114, v106, v106
	v_add_f32_e32 v113, v113, v114
	v_add_f32_e32 v112, v112, v113
	v_mov_b32_e32 v113, v112
	s_nop 1
	v_permlane16_swap_b32_e32 v112, v113
	v_add_f32_e32 v112, v112, v113
	v_mov_b32_e32 v113, v112
	s_nop 1
	v_permlane32_swap_b32_e32 v112, v113
	v_add_f32_e32 v112, v112, v113
	v_fmamk_f32 v112, v112, 0x3c800000, v190
	v_rsq_f32_e32 v112, v112
	s_waitcnt lgkmcnt(0)
	v_pk_mul_f32 v[102:103], v[102:103], v[158:159]
	v_pk_mul_f32 v[100:101], v[100:101], v[156:157]
	v_pk_mul_f32 v[98:99], v[98:99], v[154:155]
	v_pk_mul_f32 v[96:97], v[96:97], v[152:153]
	v_pk_mul_f32 v[110:111], v[110:111], v[150:151]
	v_pk_mul_f32 v[108:109], v[108:109], v[148:149]
	v_pk_mul_f32 v[106:107], v[106:107], v[146:147]
	v_pk_mul_f32 v[104:105], v[104:105], v[144:145]
	v_pk_mul_f32 v[102:103], v[102:103], v[112:113] op_sel_hi:[1,0]
	v_pk_mul_f32 v[100:101], v[100:101], v[112:113] op_sel_hi:[1,0]
	v_pk_mul_f32 v[98:99], v[98:99], v[112:113] op_sel_hi:[1,0]
	v_pk_mul_f32 v[96:97], v[96:97], v[112:113] op_sel_hi:[1,0]
	v_pk_mul_f32 v[110:111], v[110:111], v[112:113] op_sel_hi:[1,0]
	v_pk_mul_f32 v[108:109], v[108:109], v[112:113] op_sel_hi:[1,0]
	v_pk_mul_f32 v[106:107], v[106:107], v[112:113] op_sel_hi:[1,0]
	v_pk_mul_f32 v[104:105], v[104:105], v[112:113] op_sel_hi:[1,0]
; __device__ __forceinline__ float sum_x16(float v) { float a, b; swap16(v, a, b); return a + b; }
; __device__ __forceinline__ float sum_x32(float v) { float a, b; swap32(v, a, b); return a + b; }
; __device__ __forceinline__ void st16_wt(void* p, u32x4 v) { if (WT_STORES) asm volatile("global_store_dwordx4 %0, %1, off sc1\n\ts_nop 1" :: "v"(p), "v"(v) : "memory"); else *(u32x4*)p = v; }
; __device__ __forceinline__ unsigned cvt_pk_bf16(float lo, float hi) { unsigned r; asm volatile("v_cvt_pk_bf16_f32 %0, %1, %2" : "=v"(r) : "v"(lo), "v"(hi)); return r; }
;     __device__ __forceinline__ void operator()(const f32x4 (&acc)[2][2][4][2], const Unit& u, int wr, int wc, int fr, int fq, const bool reuse, PG8_LAS float* rscr, PG8_LAS const float* gains) const {
;     ...
;                 if (type < 2) {
;                     float ss = 0.f;
; #pragma unroll
;                     for (int bj = 0; bj < 2; ++bj)
; #pragma unroll
;                         for (int n = 0; n < 2; ++n) { const f32x4 x = v[bj][n]; ss += (x[0] * x[0] + x[1] * x[1]) + (x[2] * x[2] + x[3] * x[3]); }
;                     ss = sum_x16(ss); ss = sum_x32(ss);
;                     const float inv = __builtin_amdgcn_rsqf(ss * (1.0f / 64.0f) + RMS_EPS);
; #pragma unroll
;                     for (int bj = 0; bj < 2; ++bj)
; #pragma unroll
;                         for (int n = 0; n < 2; ++n) v[bj][n] = v[bj][n] * gv[bj][n] * inv;
;                 }
;                 bf16_t* p = p0 + (size_t)(8 * ai + m) * step16;
; #pragma unroll
;                 for (int bj = 0; bj < 2; ++bj) { u32x4 w; w.x = cvt_pk_bf16(v[bj][0][0], v[bj][0][1]); w.y = cvt_pk_bf16(v[bj][0][2], v[bj][0][3]); w.z = cvt_pk_bf16(v[bj][1][0], v[bj][1][1]); w.w = cvt_pk_bf16(v[bj][1][2], v[bj][1][3]);
;                     st16_wt(p + 32 * bj, w); }
.LBB0_236:
	s_nop 0
	v_lshl_add_u64 v[112:113], v[128:129], 0, s[88:89]
	s_and_b64 vcc, exec, s[38:39]
	v_cvt_pk_bf16_f32 v100, v100, v101
	v_cvt_pk_bf16_f32 v101, v102, v103
	v_cvt_pk_bf16_f32 v102, v96, v97
	v_cvt_pk_bf16_f32 v103, v98, v99
	global_store_dwordx4 v[112:113], v[100:103], off sc1
	v_cvt_pk_bf16_f32 v96, v108, v109
	v_cvt_pk_bf16_f32 v97, v110, v111
	v_cvt_pk_bf16_f32 v98, v104, v105
	v_cvt_pk_bf16_f32 v99, v106, v107
	global_store_dwordx4 v[112:113], v[96:99], off offset:64 sc1
	s_cbranch_vccnz .LBB0_238
	s_nop 0
	v_mul_f32_e32 v96, v85, v85
	v_mul_f32_e32 v97, v87, v87
	v_fmac_f32_e32 v96, v84, v84
	v_fmac_f32_e32 v97, v86, v86
	v_add_f32_e32 v96, v96, v97
	v_mul_f32_e32 v97, v81, v81
	v_mul_f32_e32 v98, v83, v83
	v_fmac_f32_e32 v97, v80, v80
	v_fmac_f32_e32 v98, v82, v82
	v_add_f32_e32 v97, v97, v98
	v_add_f32_e32 v96, v96, v97
	v_mul_f32_e32 v97, v93, v93
	v_mul_f32_e32 v98, v95, v95
	v_fmac_f32_e32 v97, v92, v92
	v_fmac_f32_e32 v98, v94, v94
	v_add_f32_e32 v97, v97, v98
	v_add_f32_e32 v96, v96, v97
	v_mul_f32_e32 v97, v89, v89
	v_mul_f32_e32 v98, v91, v91
	v_fmac_f32_e32 v97, v88, v88
	v_fmac_f32_e32 v98, v90, v90
	v_add_f32_e32 v97, v97, v98
	v_add_f32_e32 v96, v96, v97
	v_mov_b32_e32 v97, v96
	s_nop 1
	v_permlane16_swap_b32_e32 v96, v97
	v_add_f32_e32 v96, v96, v97
	v_mov_b32_e32 v97, v96
	s_nop 1
	v_permlane32_swap_b32_e32 v96, v97
	v_add_f32_e32 v96, v96, v97
	v_fmamk_f32 v96, v96, 0x3c800000, v190
	v_rsq_f32_e32 v96, v96
	s_waitcnt lgkmcnt(0)
	v_pk_mul_f32 v[86:87], v[86:87], v[158:159]
	v_pk_mul_f32 v[84:85], v[84:85], v[156:157]
	v_pk_mul_f32 v[82:83], v[82:83], v[154:155]
	v_pk_mul_f32 v[80:81], v[80:81], v[152:153]
	v_pk_mul_f32 v[94:95], v[94:95], v[150:151]
	v_pk_mul_f32 v[92:93], v[92:93], v[148:149]
	v_pk_mul_f32 v[90:91], v[90:91], v[146:147]
	v_pk_mul_f32 v[88:89], v[88:89], v[144:145]
	v_pk_mul_f32 v[86:87], v[86:87], v[96:97] op_sel_hi:[1,0]
	v_pk_mul_f32 v[84:85], v[84:85], v[96:97] op_sel_hi:[1,0]
	v_pk_mul_f32 v[82:83], v[82:83], v[96:97] op_sel_hi:[1,0]
	v_pk_mul_f32 v[80:81], v[80:81], v[96:97] op_sel_hi:[1,0]
	v_pk_mul_f32 v[94:95], v[94:95], v[96:97] op_sel_hi:[1,0]
	v_pk_mul_f32 v[92:93], v[92:93], v[96:97] op_sel_hi:[1,0]
	v_pk_mul_f32 v[90:91], v[90:91], v[96:97] op_sel_hi:[1,0]
	v_pk_mul_f32 v[88:89], v[88:89], v[96:97] op_sel_hi:[1,0]
.LBB0_238:
	s_nop 0
	v_lshl_add_u64 v[96:97], v[112:113], 0, s[88:89]
	s_and_b64 vcc, exec, s[38:39]
	v_cvt_pk_bf16_f32 v84, v84, v85
	v_cvt_pk_bf16_f32 v85, v86, v87
	v_cvt_pk_bf16_f32 v86, v80, v81
	v_cvt_pk_bf16_f32 v87, v82, v83
	global_store_dwordx4 v[96:97], v[84:87], off sc1
	v_cvt_pk_bf16_f32 v80, v92, v93
	v_cvt_pk_bf16_f32 v81, v94, v95
	v_cvt_pk_bf16_f32 v82, v88, v89
	v_cvt_pk_bf16_f32 v83, v90, v91
	global_store_dwordx4 v[96:97], v[80:83], off offset:64 sc1
	s_cbranch_vccnz .LBB0_240
	s_nop 0
	v_mul_f32_e32 v80, v69, v69
	v_mul_f32_e32 v81, v71, v71
	v_fmac_f32_e32 v80, v68, v68
	v_fmac_f32_e32 v81, v70, v70
	v_add_f32_e32 v80, v80, v81
	v_mul_f32_e32 v81, v65, v65
	v_mul_f32_e32 v82, v67, v67
	v_fmac_f32_e32 v81, v64, v64
	v_fmac_f32_e32 v82, v66, v66
	v_add_f32_e32 v81, v81, v82
	v_add_f32_e32 v80, v80, v81
	v_mul_f32_e32 v81, v77, v77
	v_mul_f32_e32 v82, v79, v79
	v_fmac_f32_e32 v81, v76, v76
	v_fmac_f32_e32 v82, v78, v78
	v_add_f32_e32 v81, v81, v82
	v_add_f32_e32 v80, v80, v81
	v_mul_f32_e32 v81, v73, v73
	v_mul_f32_e32 v82, v75, v75
	v_fmac_f32_e32 v81, v72, v72
	v_fmac_f32_e32 v82, v74, v74
	v_add_f32_e32 v81, v81, v82
	v_add_f32_e32 v80, v80, v81
	v_mov_b32_e32 v81, v80
	s_nop 1
	v_permlane16_swap_b32_e32 v80, v81
	v_add_f32_e32 v80, v80, v81
	v_mov_b32_e32 v81, v80
	s_nop 1
	v_permlane32_swap_b32_e32 v80, v81
	v_add_f32_e32 v80, v80, v81
	v_fmamk_f32 v80, v80, 0x3c800000, v190
	v_rsq_f32_e32 v80, v80
	s_waitcnt lgkmcnt(0)
	v_pk_mul_f32 v[70:71], v[70:71], v[158:159]
	v_pk_mul_f32 v[68:69], v[68:69], v[156:157]
	v_pk_mul_f32 v[66:67], v[66:67], v[154:155]
	v_pk_mul_f32 v[64:65], v[64:65], v[152:153]
	v_pk_mul_f32 v[78:79], v[78:79], v[150:151]
	v_pk_mul_f32 v[76:77], v[76:77], v[148:149]
	v_pk_mul_f32 v[74:75], v[74:75], v[146:147]
	v_pk_mul_f32 v[72:73], v[72:73], v[144:145]
	v_pk_mul_f32 v[70:71], v[70:71], v[80:81] op_sel_hi:[1,0]
	v_pk_mul_f32 v[68:69], v[68:69], v[80:81] op_sel_hi:[1,0]
	v_pk_mul_f32 v[66:67], v[66:67], v[80:81] op_sel_hi:[1,0]
	v_pk_mul_f32 v[64:65], v[64:65], v[80:81] op_sel_hi:[1,0]
	v_pk_mul_f32 v[78:79], v[78:79], v[80:81] op_sel_hi:[1,0]
	v_pk_mul_f32 v[76:77], v[76:77], v[80:81] op_sel_hi:[1,0]
	v_pk_mul_f32 v[74:75], v[74:75], v[80:81] op_sel_hi:[1,0]
	v_pk_mul_f32 v[72:73], v[72:73], v[80:81] op_sel_hi:[1,0]
; __device__ __forceinline__ float sum_x16(float v) { float a, b; swap16(v, a, b); return a + b; }
; __device__ __forceinline__ float sum_x32(float v) { float a, b; swap32(v, a, b); return a + b; }
; __device__ __forceinline__ void st16_wt(void* p, u32x4 v) { if (WT_STORES) asm volatile("global_store_dwordx4 %0, %1, off sc1\n\ts_nop 1" :: "v"(p), "v"(v) : "memory"); else *(u32x4*)p = v; }
; __device__ __forceinline__ unsigned cvt_pk_bf16(float lo, float hi) { unsigned r; asm volatile("v_cvt_pk_bf16_f32 %0, %1, %2" : "=v"(r) : "v"(lo), "v"(hi)); return r; }
;     __device__ __forceinline__ void operator()(const f32x4 (&acc)[2][2][4][2], const Unit& u, int wr, int wc, int fr, int fq, const bool reuse, PG8_LAS float* rscr, PG8_LAS const float* gains) const {
;     ...
;                 if (type < 2) {
;                     float ss = 0.f;
; #pragma unroll
;                     for (int bj = 0; bj < 2; ++bj)
; #pragma unroll
;                         for (int n = 0; n < 2; ++n) { const f32x4 x = v[bj][n]; ss += (x[0] * x[0] + x[1] * x[1]) + (x[2] * x[2] + x[3] * x[3]); }
;                     ss = sum_x16(ss); ss = sum_x32(ss);
;                     const float inv = __builtin_amdgcn_rsqf(ss * (1.0f / 64.0f) + RMS_EPS);
; #pragma unroll
;                     for (int bj = 0; bj < 2; ++bj)
; #pragma unroll
;                         for (int n = 0; n < 2; ++n) v[bj][n] = v[bj][n] * gv[bj][n] * inv;
;                 }
;                 bf16_t* p = p0 + (size_t)(8 * ai + m) * step16;
; #pragma unroll
;                 for (int bj = 0; bj < 2; ++bj) { u32x4 w; w.x = cvt_pk_bf16(v[bj][0][0], v[bj][0][1]); w.y = cvt_pk_bf16(v[bj][0][2], v[bj][0][3]); w.z = cvt_pk_bf16(v[bj][1][0], v[bj][1][1]); w.w = cvt_pk_bf16(v[bj][1][2], v[bj][1][3]);
;                     st16_wt(p + 32 * bj, w); }
.LBB0_240:
	s_nop 0
	v_mad_u64_u32 v[80:81], s[12:13], s72, 10, v[96:97]
	s_and_b64 vcc, exec, s[38:39]
	v_cvt_pk_bf16_f32 v68, v68, v69
	v_cvt_pk_bf16_f32 v69, v70, v71
	v_cvt_pk_bf16_f32 v70, v64, v65
	v_cvt_pk_bf16_f32 v71, v66, v67
	global_store_dwordx4 v[80:81], v[68:71], off sc1
	v_cvt_pk_bf16_f32 v64, v76, v77
	v_cvt_pk_bf16_f32 v65, v78, v79
	v_cvt_pk_bf16_f32 v66, v72, v73
	v_cvt_pk_bf16_f32 v67, v74, v75
	global_store_dwordx4 v[80:81], v[64:67], off offset:64 sc1
	s_cbranch_vccnz .LBB0_242
	s_nop 0
	v_mul_f32_e32 v64, v53, v53
	v_mul_f32_e32 v65, v55, v55
	v_fmac_f32_e32 v64, v52, v52
	v_fmac_f32_e32 v65, v54, v54
	v_add_f32_e32 v64, v64, v65
	v_mul_f32_e32 v65, v49, v49
	v_mul_f32_e32 v66, v51, v51
	v_fmac_f32_e32 v65, v48, v48
	v_fmac_f32_e32 v66, v50, v50
	v_add_f32_e32 v65, v65, v66
	v_add_f32_e32 v64, v64, v65
	v_mul_f32_e32 v65, v61, v61
	v_mul_f32_e32 v66, v63, v63
	v_fmac_f32_e32 v65, v60, v60
	v_fmac_f32_e32 v66, v62, v62
	v_add_f32_e32 v65, v65, v66
	v_add_f32_e32 v64, v64, v65
	v_mul_f32_e32 v65, v57, v57
	v_mul_f32_e32 v66, v59, v59
	v_fmac_f32_e32 v65, v56, v56
	v_fmac_f32_e32 v66, v58, v58
	v_add_f32_e32 v65, v65, v66
	v_add_f32_e32 v64, v64, v65
	v_mov_b32_e32 v65, v64
	s_nop 1
	v_permlane16_swap_b32_e32 v64, v65
	v_add_f32_e32 v64, v64, v65
	v_mov_b32_e32 v65, v64
	s_nop 1
	v_permlane32_swap_b32_e32 v64, v65
	v_add_f32_e32 v64, v64, v65
	v_fmamk_f32 v64, v64, 0x3c800000, v190
	v_rsq_f32_e32 v64, v64
	s_waitcnt lgkmcnt(0)
	v_pk_mul_f32 v[54:55], v[54:55], v[158:159]
	v_pk_mul_f32 v[52:53], v[52:53], v[156:157]
	v_pk_mul_f32 v[50:51], v[50:51], v[154:155]
	v_pk_mul_f32 v[48:49], v[48:49], v[152:153]
	v_pk_mul_f32 v[62:63], v[62:63], v[150:151]
	v_pk_mul_f32 v[60:61], v[60:61], v[148:149]
	v_pk_mul_f32 v[58:59], v[58:59], v[146:147]
	v_pk_mul_f32 v[56:57], v[56:57], v[144:145]
	v_pk_mul_f32 v[54:55], v[54:55], v[64:65] op_sel_hi:[1,0]
	v_pk_mul_f32 v[52:53], v[52:53], v[64:65] op_sel_hi:[1,0]
	v_pk_mul_f32 v[50:51], v[50:51], v[64:65] op_sel_hi:[1,0]
	v_pk_mul_f32 v[48:49], v[48:49], v[64:65] op_sel_hi:[1,0]
	v_pk_mul_f32 v[62:63], v[62:63], v[64:65] op_sel_hi:[1,0]
	v_pk_mul_f32 v[60:61], v[60:61], v[64:65] op_sel_hi:[1,0]
	v_pk_mul_f32 v[58:59], v[58:59], v[64:65] op_sel_hi:[1,0]
	v_pk_mul_f32 v[56:57], v[56:57], v[64:65] op_sel_hi:[1,0]
.LBB0_242:
	s_nop 0
	v_lshl_add_u64 v[64:65], v[80:81], 0, s[88:89]
	s_and_b64 vcc, exec, s[38:39]
	v_cvt_pk_bf16_f32 v52, v52, v53
	v_cvt_pk_bf16_f32 v53, v54, v55
	v_cvt_pk_bf16_f32 v54, v48, v49
	v_cvt_pk_bf16_f32 v55, v50, v51
	global_store_dwordx4 v[64:65], v[52:55], off sc1
	v_cvt_pk_bf16_f32 v48, v60, v61
	v_cvt_pk_bf16_f32 v49, v62, v63
	v_cvt_pk_bf16_f32 v50, v56, v57
	v_cvt_pk_bf16_f32 v51, v58, v59
	global_store_dwordx4 v[64:65], v[48:51], off offset:64 sc1
	s_cbranch_vccnz .LBB0_244
	s_nop 0
	v_mul_f32_e32 v48, v37, v37
	v_mul_f32_e32 v49, v39, v39
	v_fmac_f32_e32 v48, v36, v36
	v_fmac_f32_e32 v49, v38, v38
	v_add_f32_e32 v48, v48, v49
	v_mul_f32_e32 v49, v33, v33
	v_mul_f32_e32 v50, v35, v35
	v_fmac_f32_e32 v49, v32, v32
	v_fmac_f32_e32 v50, v34, v34
	v_add_f32_e32 v49, v49, v50
	v_add_f32_e32 v48, v48, v49
	v_mul_f32_e32 v49, v45, v45
	v_mul_f32_e32 v50, v47, v47
	v_fmac_f32_e32 v49, v44, v44
	v_fmac_f32_e32 v50, v46, v46
	v_add_f32_e32 v49, v49, v50
	v_add_f32_e32 v48, v48, v49
	v_mul_f32_e32 v49, v41, v41
	v_mul_f32_e32 v50, v43, v43
	v_fmac_f32_e32 v49, v40, v40
	v_fmac_f32_e32 v50, v42, v42
	v_add_f32_e32 v49, v49, v50
	v_add_f32_e32 v48, v48, v49
	v_mov_b32_e32 v49, v48
	s_nop 1
	v_permlane16_swap_b32_e32 v48, v49
	v_add_f32_e32 v48, v48, v49
	v_mov_b32_e32 v49, v48
	s_nop 1
	v_permlane32_swap_b32_e32 v48, v49
	v_add_f32_e32 v48, v48, v49
	v_fmamk_f32 v48, v48, 0x3c800000, v190
	v_rsq_f32_e32 v48, v48
	s_waitcnt lgkmcnt(0)
	v_pk_mul_f32 v[38:39], v[38:39], v[158:159]
	v_pk_mul_f32 v[36:37], v[36:37], v[156:157]
	v_pk_mul_f32 v[34:35], v[34:35], v[154:155]
	v_pk_mul_f32 v[32:33], v[32:33], v[152:153]
	v_pk_mul_f32 v[46:47], v[46:47], v[150:151]
	v_pk_mul_f32 v[44:45], v[44:45], v[148:149]
	v_pk_mul_f32 v[42:43], v[42:43], v[146:147]
	v_pk_mul_f32 v[40:41], v[40:41], v[144:145]
	v_pk_mul_f32 v[38:39], v[38:39], v[48:49] op_sel_hi:[1,0]
	v_pk_mul_f32 v[36:37], v[36:37], v[48:49] op_sel_hi:[1,0]
	v_pk_mul_f32 v[34:35], v[34:35], v[48:49] op_sel_hi:[1,0]
	v_pk_mul_f32 v[32:33], v[32:33], v[48:49] op_sel_hi:[1,0]
	v_pk_mul_f32 v[46:47], v[46:47], v[48:49] op_sel_hi:[1,0]
	v_pk_mul_f32 v[44:45], v[44:45], v[48:49] op_sel_hi:[1,0]
	v_pk_mul_f32 v[42:43], v[42:43], v[48:49] op_sel_hi:[1,0]
	v_pk_mul_f32 v[40:41], v[40:41], v[48:49] op_sel_hi:[1,0]
;     __device__ __forceinline__ void side_finish(const Side& s, int lane) const {
;         if (MODE == 0 && s.row < xrows) {
;             float q = 0.f;
; #pragma unroll
;             for (int j = 0; j < 4; ++j) q += (s.v[j][0] * s.v[j][0] + s.v[j][1] * s.v[j][1]) + (s.v[j][2] * s.v[j][2] + s.v[j][3] * s.v[j][3]);
;             const float rstd = __builtin_amdgcn_rsqf(wave_sum(q) * (1.0f / 1024.0f) + 1e-6f);
;             const bool odd = lane & 1;
;             bf16_t* orow = xd + (size_t)s.row * 1024 + 4 * (lane & ~1);
; #pragma unroll
;             for (int jp = 0; jp < 2; ++jp) {
;                 const int ja = 2 * jp, jb = 2 * jp + 1;
;                 const unsigned pax = cvt_pk_bf16(s.v[ja][0] * rstd, s.v[ja][1] * rstd), pay = cvt_pk_bf16(s.v[ja][2] * rstd, s.v[ja][3] * rstd);
;                 const unsigned pbx = cvt_pk_bf16(s.v[jb][0] * rstd, s.v[jb][1] * rstd), pby = cvt_pk_bf16(s.v[jb][2] * rstd, s.v[jb][3] * rstd);
;                 const unsigned rx = (unsigned)__builtin_amdgcn_update_dpp(0, (int)(odd ? pax : pbx), 0xB1, 0xF, 0xF, true), ry = (unsigned)__builtin_amdgcn_update_dpp(0, (int)(odd ? pay : pby), 0xB1, 0xF, 0xF, true);
;     __device__ __forceinline__ void operator()(const f32x4 (&acc)[2][2][4][2], const Unit& u, int wr, int wc, int fr, int fq, const bool reuse, PG8_LAS float* rscr, PG8_LAS const float* gains) const {
;     ...
;                 if (type < 2) {
;                     float ss = 0.f;
; #pragma unroll
;                     for (int bj = 0; bj < 2; ++bj)
; #pragma unroll
;                         for (int n = 0; n < 2; ++n) { const f32x4 x = v[bj][n]; ss += (x[0] * x[0] + x[1] * x[1]) + (x[2] * x[2] + x[3] * x[3]); }
;                     ss = sum_x16(ss); ss = sum_x32(ss);
;                     const float inv = __builtin_amdgcn_rsqf(ss * (1.0f / 64.0f) + RMS_EPS);
; #pragma unroll
;                     for (int bj = 0; bj < 2; ++bj)
; #pragma unroll
;                         for (int n = 0; n < 2; ++n) v[bj][n] = v[bj][n] * gv[bj][n] * inv;
;                 }
;                 bf16_t* p = p0 + (size_t)(8 * ai + m) * step16;
; #pragma unroll
;                 for (int bj = 0; bj < 2; ++bj) { u32x4 w; w.x = cvt_pk_bf16(v[bj][0][0], v[bj][0][1]); w.y = cvt_pk_bf16(v[bj][0][2], v[bj][0][3]); w.z = cvt_pk_bf16(v[bj][1][0], v[bj][1][1]); w.w = cvt_pk_bf16(v[bj][1][2], v[bj][1][3]);
;                     st16_wt(p + 32 * bj, w); }
.LBB0_244:
	s_nop 0
	v_lshl_add_u64 v[48:49], v[64:65], 0, s[88:89]
	s_and_b64 vcc, exec, s[38:39]
	v_cvt_pk_bf16_f32 v36, v36, v37
	v_cvt_pk_bf16_f32 v37, v38, v39
	v_cvt_pk_bf16_f32 v38, v32, v33
	v_cvt_pk_bf16_f32 v39, v34, v35
	global_store_dwordx4 v[48:49], v[36:39], off sc1
	v_cvt_pk_bf16_f32 v32, v44, v45
	v_cvt_pk_bf16_f32 v33, v46, v47
	v_cvt_pk_bf16_f32 v34, v40, v41
	v_cvt_pk_bf16_f32 v35, v42, v43
	global_store_dwordx4 v[48:49], v[32:35], off offset:64 sc1
	s_cbranch_vccnz .LBB0_246
	s_nop 0
	v_mul_f32_e32 v32, v21, v21
	v_mul_f32_e32 v33, v23, v23
	v_fmac_f32_e32 v32, v20, v20
	v_fmac_f32_e32 v33, v22, v22
	v_add_f32_e32 v32, v32, v33
	v_mul_f32_e32 v33, v17, v17
	v_mul_f32_e32 v34, v19, v19
	v_fmac_f32_e32 v33, v16, v16
	v_fmac_f32_e32 v34, v18, v18
	v_add_f32_e32 v33, v33, v34
	v_add_f32_e32 v32, v32, v33
	v_mul_f32_e32 v33, v25, v25
	v_mul_f32_e32 v34, v27, v27
	v_fmac_f32_e32 v33, v24, v24
	v_fmac_f32_e32 v34, v26, v26
	v_add_f32_e32 v33, v33, v34
	v_add_f32_e32 v32, v32, v33
	v_mul_f32_e32 v33, v29, v29
	v_mul_f32_e32 v34, v31, v31
	v_fmac_f32_e32 v33, v28, v28
	v_fmac_f32_e32 v34, v30, v30
	v_add_f32_e32 v33, v33, v34
	v_add_f32_e32 v32, v32, v33
	v_mov_b32_e32 v33, v32
	s_nop 1
	v_permlane16_swap_b32_e32 v32, v33
	v_add_f32_e32 v32, v32, v33
	v_mov_b32_e32 v33, v32
	s_nop 1
	v_permlane32_swap_b32_e32 v32, v33
	v_add_f32_e32 v32, v32, v33
	v_fmamk_f32 v32, v32, 0x3c800000, v190
	v_rsq_f32_e32 v32, v32
	s_waitcnt lgkmcnt(0)
	v_pk_mul_f32 v[22:23], v[22:23], v[158:159]
	v_pk_mul_f32 v[20:21], v[20:21], v[156:157]
	v_pk_mul_f32 v[18:19], v[18:19], v[154:155]
	v_pk_mul_f32 v[16:17], v[16:17], v[152:153]
	v_pk_mul_f32 v[26:27], v[26:27], v[150:151]
	v_pk_mul_f32 v[24:25], v[24:25], v[148:149]
	v_pk_mul_f32 v[30:31], v[30:31], v[146:147]
	v_pk_mul_f32 v[28:29], v[28:29], v[144:145]
	v_pk_mul_f32 v[22:23], v[22:23], v[32:33] op_sel_hi:[1,0]
	v_pk_mul_f32 v[20:21], v[20:21], v[32:33] op_sel_hi:[1,0]
	v_pk_mul_f32 v[18:19], v[18:19], v[32:33] op_sel_hi:[1,0]
	v_pk_mul_f32 v[16:17], v[16:17], v[32:33] op_sel_hi:[1,0]
	v_pk_mul_f32 v[26:27], v[26:27], v[32:33] op_sel_hi:[1,0]
	v_pk_mul_f32 v[24:25], v[24:25], v[32:33] op_sel_hi:[1,0]
	v_pk_mul_f32 v[30:31], v[30:31], v[32:33] op_sel_hi:[1,0]
	v_pk_mul_f32 v[28:29], v[28:29], v[32:33] op_sel_hi:[1,0]
.LBB0_246:
	s_nop 0
	v_lshl_add_u64 v[32:33], v[48:49], 0, s[88:89]
	s_andn2_b64 vcc, exec, s[80:81]
	v_cvt_pk_bf16_f32 v20, v20, v21
	v_cvt_pk_bf16_f32 v21, v22, v23
	v_cvt_pk_bf16_f32 v22, v16, v17
	v_cvt_pk_bf16_f32 v23, v18, v19
	global_store_dwordx4 v[32:33], v[20:23], off sc1
	v_cvt_pk_bf16_f32 v16, v24, v25
	v_cvt_pk_bf16_f32 v17, v26, v27
	v_cvt_pk_bf16_f32 v18, v28, v29
	v_cvt_pk_bf16_f32 v19, v30, v31
	global_store_dwordx4 v[32:33], v[16:19], off offset:64 sc1
	s_cbranch_vccnz .LBB0_248
	s_waitcnt vmcnt(16)
	v_mul_f32_e32 v16, v13, v13
	v_mul_f32_e32 v17, v15, v15
	v_fmac_f32_e32 v16, v12, v12
	v_fmac_f32_e32 v17, v14, v14
	v_add_f32_e32 v16, v16, v17
	v_mul_f32_e32 v17, v9, v9
	v_mul_f32_e32 v18, v11, v11
	v_fmac_f32_e32 v17, v8, v8
	v_fmac_f32_e32 v18, v10, v10
	v_add_f32_e32 v17, v17, v18
	v_add_f32_e32 v16, v17, v16
	v_mul_f32_e32 v17, v5, v5
	v_mul_f32_e32 v18, v7, v7
	v_fmac_f32_e32 v17, v4, v4
	v_fmac_f32_e32 v18, v6, v6
	v_add_f32_e32 v17, v17, v18
	v_add_f32_e32 v16, v17, v16
	v_mul_f32_e32 v17, v1, v1
	v_mul_f32_e32 v18, v3, v3
	v_fmac_f32_e32 v17, v0, v0
	v_fmac_f32_e32 v18, v2, v2
	v_add_f32_e32 v17, v17, v18
	v_add_f32_e32 v16, v17, v16
	s_ashr_i32 s77, s76, 31
	s_lshl_b64 s[12:13], s[76:77], 11
	v_add_f32_dpp v16, v16, v16 quad_perm:[1,0,3,2] row_mask:0xf bank_mask:0xf bound_ctrl:1
	v_lshl_add_u64 v[20:21], v[176:177], 0, s[12:13]
	v_mov_b32_e32 v183, v161
	v_add_f32_dpp v16, v16, v16 quad_perm:[2,3,0,1] row_mask:0xf bank_mask:0xf bound_ctrl:1
	v_mov_b32_e32 v185, v161
	s_nop 0
	v_add_f32_dpp v16, v16, v16 row_half_mirror row_mask:0xf bank_mask:0xf bound_ctrl:1
	s_nop 1
	v_add_f32_dpp v16, v16, v16 row_mirror row_mask:0xf bank_mask:0xf bound_ctrl:1
	v_mov_b32_e32 v17, v16
	s_nop 1
	v_permlane16_swap_b32_e32 v16, v17
	v_add_f32_e32 v16, v16, v17
	v_mov_b32_e32 v17, v16
	s_nop 1
	v_permlane32_swap_b32_e32 v16, v17
	v_add_f32_e32 v16, v16, v17
	v_fmamk_f32 v16, v16, 0x3a800000, v190
	v_rsq_f32_e32 v24, v16
	s_nop 0
	v_mul_f32_e32 v16, v12, v24
	v_mul_f32_e32 v17, v13, v24
	v_cvt_pk_bf16_f32 v16, v16, v17
	v_mul_f32_e32 v17, v14, v24
	v_mul_f32_e32 v18, v15, v24
	v_cvt_pk_bf16_f32 v17, v17, v18
	v_mul_f32_e32 v18, v8, v24
	v_mul_f32_e32 v19, v9, v24
	v_cvt_pk_bf16_f32 v18, v18, v19
	v_mul_f32_e32 v19, v10, v24
	v_mul_f32_e32 v22, v11, v24
	v_cvt_pk_bf16_f32 v19, v19, v22
	v_cndmask_b32_e64 v22, v16, v18, s[34:35]
	v_cndmask_b32_e64 v23, v17, v19, s[34:35]
	s_nop 0
	v_mov_b32_dpp v22, v22 quad_perm:[1,0,3,2] row_mask:0xf bank_mask:0xf bound_ctrl:1
	v_mov_b32_dpp v23, v23 quad_perm:[1,0,3,2] row_mask:0xf bank_mask:0xf bound_ctrl:1
	v_cndmask_b32_e64 v16, v22, v16, s[34:35]
	v_cndmask_b32_e64 v17, v23, v17, s[34:35]
	v_cndmask_b32_e64 v18, v18, v22, s[34:35]
	v_cndmask_b32_e64 v19, v19, v23, s[34:35]
	v_lshl_add_u64 v[22:23], v[20:21], 0, v[182:183]
	global_store_dwordx4 v[22:23], v[16:19], off
	v_mul_f32_e32 v22, v3, v24
	v_lshl_add_u64 v[20:21], v[20:21], 0, v[184:185]
	v_mul_f32_e32 v16, v4, v24
	v_mul_f32_e32 v17, v5, v24
	v_cvt_pk_bf16_f32 v16, v16, v17
	v_mul_f32_e32 v17, v6, v24
	v_mul_f32_e32 v18, v7, v24
	v_cvt_pk_bf16_f32 v17, v17, v18
	v_mul_f32_e32 v18, v0, v24
	v_mul_f32_e32 v19, v1, v24
	v_cvt_pk_bf16_f32 v18, v18, v19
	v_mul_f32_e32 v19, v2, v24
	v_cvt_pk_bf16_f32 v19, v19, v22
	v_cndmask_b32_e64 v22, v16, v18, s[34:35]
	v_cndmask_b32_e64 v23, v17, v19, s[34:35]
	s_nop 0
	v_mov_b32_dpp v22, v22 quad_perm:[1,0,3,2] row_mask:0xf bank_mask:0xf bound_ctrl:1
	v_mov_b32_dpp v23, v23 quad_perm:[1,0,3,2] row_mask:0xf bank_mask:0xf bound_ctrl:1
	v_cndmask_b32_e64 v16, v22, v16, s[34:35]
	v_cndmask_b32_e64 v17, v23, v17, s[34:35]
	v_cndmask_b32_e64 v18, v18, v22, s[34:35]
	v_cndmask_b32_e64 v19, v19, v23, s[34:35]
	global_store_dwordx4 v[20:21], v[16:19], off
